# norm phases: first four wave-reduction steps as DPP adds instead of LDS shuffles
# speedup vs baseline: 1.0100x; 1.0025x over previous
; DI unsigned pk2(float lo, float hi) { f32x2 v = {lo, hi}; bf16x2_t b = __builtin_convertvector(v, bf16x2_t); return __builtin_bit_cast(unsigned, b); }
; DI void norm_row16_finish(int m, const f32x4 (&v)[4], float s, const float* gain, const float* mod, int shofs, int scofs, bf16_t* XN, int lane) {
;     const float* mb = mod + (size_t)row_batch(m) * NMOD;
;     const float inv = __builtin_amdgcn_rsqf(s * (1.f / D) + EPS);
; #pragma unroll
;     for (int j = 0; j < 2; ++j) {
;         const int c = 8 * (64 * j + lane);
;         u32x4 w;
; #pragma unroll
;         for (int q = 0; q < 2; ++q) {
;             const f32x4 g4 = *(const f32x4*)(gain + c + 4 * q), sc4 = *(const f32x4*)(mb + scofs + c + 4 * q), sh4 = *(const f32x4*)(mb + shofs + c + 4 * q);
;             const f32x4 o = v[2 * j + q] * inv * g4 * (sc4 + 1.f) + sh4;
;             if (q == 0) { w.x = pk2(o[0], o[1]); w.y = pk2(o[2], o[3]); } else { w.z = pk2(o[0], o[1]); w.w = pk2(o[2], o[3]); }
;         }
;         *(u32x4*)(XN + (size_t)m * D + c) = w;
;     }
; DI void norm_phase_b16(const bf16_t* src, const float* gain, const float* mod, int shofs, int scofs, bf16_t* XN, int wave, int lane) {
;     ...
;     for (int m = gw; m < M; m += 2 * NGW) {
;         const int m2 = m + NGW; const bool two = m2 < M; const int mb2 = two ? m2 : m;
;         f32x4 va[4], vb[4]; float sa = 0.f, sb = 0.f;
; #pragma unroll
;         for (int j = 0; j < 2; ++j) {
;             const u32x4 a = *(const u32x4*)(src + (size_t)m * D + 8 * (64 * j + lane)), b = *(const u32x4*)(src + (size_t)mb2 * D + 8 * (64 * j + lane));
;             u32x2 t; t.x = a.x; t.y = a.y; va[2 * j] = bf4(t); t.x = a.z; t.y = a.w; va[2 * j + 1] = bf4(t);
;             t.x = b.x; t.y = b.y; vb[2 * j] = bf4(t); t.x = b.z; t.y = b.w; vb[2 * j + 1] = bf4(t);
;         }
; #pragma unroll
;         for (int j = 0; j < 4; ++j) { sa += (va[j][0] * va[j][0] + va[j][1] * va[j][1]) + (va[j][2] * va[j][2] + va[j][3] * va[j][3]); sb += (vb[j][0] * vb[j][0] + vb[j][1] * vb[j][1]) + (vb[j][2] * vb[j][2] + vb[j][3] * vb[j][3]); }
; #pragma unroll
;         for (int o = 1; o < 64; o <<= 1) { sa += __shfl_xor(sa, o); sb += __shfl_xor(sb, o); }
;         norm_row16_finish(m, va, sa, gain, mod, shofs, scofs, XN, lane);
;         if (two) norm_row16_finish(m2, vb, sb, gain, mod, shofs, scofs, XN, lane);
.LBB0_671:
	global_load_dwordx4 v[10:13], v[8:9], off offset:1024
	global_load_dwordx4 v[14:17], v[8:9], off
	s_add_i32 s10, s35, s7
	s_cmp_lt_i32 s10, 0x8800
	s_cselect_b32 s12, s10, s7
	s_add_i32 s14, s7, 0xffff8000
	s_ashr_i32 s13, s12, 31
	s_lshr_b32 s14, s14, 6
	s_ashr_i32 s11, s7, 13
	s_lshl_b64 s[12:13], s[12:13], 11
	s_add_i32 s14, s14, 4
	s_cmp_lt_i32 s7, 0x8000
	s_cselect_b32 s11, s11, s14
	s_waitcnt lgkmcnt(0)
	v_lshl_add_u64 v[36:37], v[4:5], 0, s[12:13]
	s_mul_hi_i32 s12, s11, 0x9000
	s_mul_i32 s11, s11, 0x9000
	s_add_u32 s14, s30, s11
	s_addc_u32 s15, s31, s12
	s_lshl_b32 s11, s17, 2
	s_add_u32 s12, s14, s11
	v_lshlrev_b32_e32 v31, 2, v0
	s_addc_u32 s13, s15, 0
	global_load_dwordx4 v[18:21], v[2:3], off offset:16
	global_load_dwordx4 v[22:25], v[2:3], off
	global_load_dwordx4 v[32:35], v[36:37], off
	s_nop 0
	global_load_dwordx4 v[36:39], v[36:37], off offset:1024
	s_nop 0
	global_load_dwordx4 v[40:43], v31, s[12:13] offset:16
	global_load_dwordx4 v[44:47], v31, s[12:13]
	s_lshl_b32 s18, s16, 2
	s_add_u32 s14, s14, s18
	s_addc_u32 s15, s15, 0
	global_load_dwordx4 v[48:51], v31, s[14:15] offset:16
	global_load_dwordx4 v[52:55], v31, s[14:15]
	s_mov_b32 s19, 0xe9c00000
	s_cmp_gt_i32 s10, 0x87ff
	s_waitcnt vmcnt(9)
	v_lshlrev_b32_e32 v64, 16, v12
	v_and_b32_e32 v76, 0xffff0000, v12
	v_lshlrev_b32_e32 v66, 16, v13
	v_and_b32_e32 v67, 0xffff0000, v13
	s_waitcnt vmcnt(8)
	v_lshlrev_b32_e32 v12, 16, v14
	v_and_b32_e32 v13, 0xffff0000, v14
	v_lshlrev_b32_e32 v14, 16, v15
	v_and_b32_e32 v15, 0xffff0000, v15
	v_lshlrev_b32_e32 v57, 16, v17
	v_lshlrev_b32_e32 v56, 16, v16
	v_and_b32_e32 v17, 0xffff0000, v17
	v_and_b32_e32 v16, 0xffff0000, v16
	v_lshlrev_b32_e32 v68, 16, v10
	v_and_b32_e32 v69, 0xffff0000, v10
	v_mul_f32_e32 v10, v12, v12
	v_mul_f32_e32 v58, v14, v14
	v_lshlrev_b32_e32 v70, 16, v11
	v_and_b32_e32 v71, 0xffff0000, v11
	v_pk_mul_f32 v[60:61], v[16:17], v[16:17]
	v_pk_fma_f32 v[10:11], v[12:13], v[12:13], v[10:11] op_sel_hi:[1,1,0]
	v_pk_fma_f32 v[58:59], v[14:15], v[14:15], v[58:59] op_sel_hi:[1,1,0]
	v_mul_f32_e32 v62, v68, v68
	v_mul_f32_e32 v72, v70, v70
	v_mov_b32_e32 v74, v64
	v_pk_fma_f32 v[60:61], v[56:57], v[56:57], v[60:61]
	v_mov_b32_e32 v65, v11
	v_mov_b32_e32 v75, v59
	v_pk_fma_f32 v[62:63], v[68:69], v[68:69], v[62:63] op_sel_hi:[1,1,0]
	v_pk_fma_f32 v[72:73], v[70:71], v[70:71], v[72:73] op_sel_hi:[1,1,0]
	v_pk_add_f32 v[60:61], v[60:61], v[60:61] op_sel_hi:[0,1]
	v_pk_add_f32 v[10:11], v[10:11], v[58:59]
	v_pk_mul_f32 v[58:59], v[64:65], v[74:75]
	v_mul_f32_e32 v62, v66, v66
	v_mul_f32_e32 v72, v67, v67
	v_mul_f32_e32 v60, v76, v76
	v_mov_b32_e32 v59, v11
	v_pk_add_f32 v[62:63], v[62:63], v[72:73]
	v_pk_add_f32 v[10:11], v[58:59], v[60:61]
	s_waitcnt vmcnt(2)
	v_pk_add_f32 v[44:45], v[44:45], 1.0 op_sel_hi:[1,0]
	v_pk_add_f32 v[10:11], v[10:11], v[62:63]
	v_pk_add_f32 v[42:43], v[42:43], 1.0 op_sel_hi:[1,0]
	v_add_f32_e32 v10, v10, v11
	v_pk_add_f32 v[40:41], v[40:41], 1.0 op_sel_hi:[1,0]
	v_add_co_u32_e32 v58, vcc, s19, v8
	v_mov_b32_e32 v65, v76
	s_waitcnt lgkmcnt(0)
	s_nop 1
	v_add_f32_dpp v10, v10, v10 quad_perm:[1,0,3,2] row_mask:0xf bank_mask:0xf
	v_addc_co_u32_e32 v59, vcc, -1, v9, vcc
	s_waitcnt lgkmcnt(0)
	s_nop 1
	v_add_f32_dpp v10, v10, v10 quad_perm:[2,3,0,1] row_mask:0xf bank_mask:0xf
	s_waitcnt lgkmcnt(0)
	s_nop 1
	v_add_f32_dpp v10, v10, v10 row_half_mirror row_mask:0xf bank_mask:0xf
	s_waitcnt lgkmcnt(0)
	s_nop 1
	v_add_f32_dpp v10, v10, v10 row_mirror row_mask:0xf bank_mask:0xf
	ds_bpermute_b32 v11, v29, v10
	s_waitcnt lgkmcnt(0)
	v_add_f32_e32 v60, v10, v11
	ds_bpermute_b32 v61, v30, v60
	v_mov_b32_e32 v10, v57
	v_mov_b32_e32 v11, v17
	v_mov_b32_e32 v57, v16
	v_pk_add_f32 v[16:17], v[46:47], 1.0 op_sel_hi:[1,0]
	s_waitcnt lgkmcnt(0)
	v_add_f32_e32 v46, v60, v61
	v_fmamk_f32 v46, v46, 0x3a800000, v195
	v_rsq_f32_e32 v72, v46
	s_nop 0
	v_pk_mul_f32 v[14:15], v[14:15], v[72:73] op_sel_hi:[1,0]
	v_pk_mul_f32 v[12:13], v[12:13], v[72:73] op_sel_hi:[1,0]
	v_pk_mul_f32 v[10:11], v[10:11], v[72:73] op_sel_hi:[1,0]
	v_pk_mul_f32 v[46:47], v[56:57], v[72:73] op_sel_hi:[1,0]
	v_pk_mul_f32 v[12:13], v[22:23], v[12:13]
	v_pk_mul_f32 v[14:15], v[24:25], v[14:15]
	v_pk_mul_f32 v[18:19], v[18:19], v[46:47]
	v_pk_mul_f32 v[10:11], v[20:21], v[10:11]
	s_waitcnt vmcnt(0)
	v_pk_fma_f32 v[14:15], v[16:17], v[14:15], v[54:55]
	v_pk_fma_f32 v[12:13], v[44:45], v[12:13], v[52:53]
	v_pk_fma_f32 v[16:17], v[42:43], v[10:11], v[50:51]
	v_pk_fma_f32 v[18:19], v[40:41], v[18:19], v[48:49]
	v_cvt_pk_bf16_f32 v10, v12, v13
	v_cvt_pk_bf16_f32 v11, v14, v15
	v_cvt_pk_bf16_f32 v12, v18, v19
	v_cvt_pk_bf16_f32 v13, v16, v17
	global_store_dwordx4 v[58:59], v[10:13], off
	global_load_dwordx4 v[40:43], v31, s[12:13] offset:2048
	global_load_dwordx4 v[48:51], v31, s[12:13] offset:2064
	global_load_dwordx4 v[44:47], v[2:3], off offset:2048
	global_load_dwordx4 v[52:55], v[2:3], off offset:2064
	s_nop 0
	global_load_dwordx4 v[56:59], v31, s[14:15] offset:2064
	global_load_dwordx4 v[60:63], v31, s[14:15] offset:2048
	v_and_b32_e32 v21, 0xffff0000, v32
	v_and_b32_e32 v25, 0xffff0000, v33
	v_and_b32_e32 v19, 0xffff0000, v34
	v_and_b32_e32 v23, 0xffff0000, v35
	v_lshlrev_b32_e32 v20, 16, v32
	v_lshlrev_b32_e32 v24, 16, v33
	v_lshlrev_b32_e32 v18, 16, v34
	v_lshlrev_b32_e32 v22, 16, v35
	v_and_b32_e32 v15, 0xffff0000, v36
	v_and_b32_e32 v17, 0xffff0000, v37
	v_mul_f32_e32 v32, v21, v21
	v_mul_f32_e32 v33, v25, v25
	v_mul_f32_e32 v34, v19, v19
	v_mul_f32_e32 v35, v23, v23
	v_lshlrev_b32_e32 v14, 16, v36
	v_lshlrev_b32_e32 v16, 16, v37
	v_and_b32_e32 v11, 0xffff0000, v38
	v_and_b32_e32 v13, 0xffff0000, v39
	v_mul_f32_e32 v36, v15, v15
	v_mul_f32_e32 v37, v17, v17
	v_fmac_f32_e32 v32, v20, v20
	v_fmac_f32_e32 v33, v24, v24
	v_fmac_f32_e32 v34, v18, v18
	v_fmac_f32_e32 v35, v22, v22
	v_lshlrev_b32_e32 v10, 16, v38
	v_lshlrev_b32_e32 v12, 16, v39
	v_mul_f32_e32 v38, v11, v11
	v_mul_f32_e32 v39, v13, v13
	v_fmac_f32_e32 v36, v14, v14
	v_fmac_f32_e32 v37, v16, v16
	v_add_f32_e32 v32, v32, v33
	v_add_f32_e32 v33, v34, v35
	v_fmac_f32_e32 v38, v10, v10
	v_fmac_f32_e32 v39, v12, v12
	v_add_f32_e32 v34, v36, v37
	v_add_f32_e32 v32, v32, v33
	v_add_f32_e32 v35, v38, v39
	v_add_f32_e32 v32, v32, v34
	v_add_f32_e32 v32, v35, v32
	v_pk_mul_f32 v[34:35], v[70:71], v[72:73] op_sel_hi:[1,0]
	v_pk_mul_f32 v[36:37], v[68:69], v[72:73] op_sel_hi:[1,0]
	v_pk_mul_f32 v[66:67], v[66:67], v[72:73] op_sel_hi:[1,0]
	v_pk_mul_f32 v[64:65], v[64:65], v[72:73] op_sel_hi:[1,0]
	s_waitcnt lgkmcnt(0)
; DI unsigned pk2(float lo, float hi) { f32x2 v = {lo, hi}; bf16x2_t b = __builtin_convertvector(v, bf16x2_t); return __builtin_bit_cast(unsigned, b); }
; DI void norm_row16_finish(int m, const f32x4 (&v)[4], float s, const float* gain, const float* mod, int shofs, int scofs, bf16_t* XN, int lane) {
;     const float* mb = mod + (size_t)row_batch(m) * NMOD;
;     const float inv = __builtin_amdgcn_rsqf(s * (1.f / D) + EPS);
; #pragma unroll
;     for (int j = 0; j < 2; ++j) {
;         const int c = 8 * (64 * j + lane);
;         u32x4 w;
; #pragma unroll
;         for (int q = 0; q < 2; ++q) {
;             const f32x4 g4 = *(const f32x4*)(gain + c + 4 * q), sc4 = *(const f32x4*)(mb + scofs + c + 4 * q), sh4 = *(const f32x4*)(mb + shofs + c + 4 * q);
;             const f32x4 o = v[2 * j + q] * inv * g4 * (sc4 + 1.f) + sh4;
;             if (q == 0) { w.x = pk2(o[0], o[1]); w.y = pk2(o[2], o[3]); } else { w.z = pk2(o[0], o[1]); w.w = pk2(o[2], o[3]); }
;         }
;         *(u32x4*)(XN + (size_t)m * D + c) = w;
;     }
; DI void norm_phase_b16(const bf16_t* src, const float* gain, const float* mod, int shofs, int scofs, bf16_t* XN, int wave, int lane) {
;     ...
;     for (int m = gw; m < M; m += 2 * NGW) {
;         const int m2 = m + NGW; const bool two = m2 < M; const int mb2 = two ? m2 : m;
;         f32x4 va[4], vb[4]; float sa = 0.f, sb = 0.f;
; #pragma unroll
;         for (int j = 0; j < 2; ++j) {
;             const u32x4 a = *(const u32x4*)(src + (size_t)m * D + 8 * (64 * j + lane)), b = *(const u32x4*)(src + (size_t)mb2 * D + 8 * (64 * j + lane));
;             u32x2 t; t.x = a.x; t.y = a.y; va[2 * j] = bf4(t); t.x = a.z; t.y = a.w; va[2 * j + 1] = bf4(t);
;             t.x = b.x; t.y = b.y; vb[2 * j] = bf4(t); t.x = b.z; t.y = b.w; vb[2 * j + 1] = bf4(t);
;         }
; #pragma unroll
;         for (int j = 0; j < 4; ++j) { sa += (va[j][0] * va[j][0] + va[j][1] * va[j][1]) + (va[j][2] * va[j][2] + va[j][3] * va[j][3]); sb += (vb[j][0] * vb[j][0] + vb[j][1] * vb[j][1]) + (vb[j][2] * vb[j][2] + vb[j][3] * vb[j][3]); }
; #pragma unroll
;         for (int o = 1; o < 64; o <<= 1) { sa += __shfl_xor(sa, o); sb += __shfl_xor(sb, o); }
;         norm_row16_finish(m, va, sa, gain, mod, shofs, scofs, XN, lane);
;         if (two) norm_row16_finish(m2, vb, sb, gain, mod, shofs, scofs, XN, lane);
	s_nop 1
	v_add_f32_dpp v32, v32, v32 quad_perm:[1,0,3,2] row_mask:0xf bank_mask:0xf
	v_add_co_u32_e32 v38, vcc, 0xe9c01000, v8
	s_waitcnt lgkmcnt(0)
	s_nop 1
	v_add_f32_dpp v32, v32, v32 quad_perm:[2,3,0,1] row_mask:0xf bank_mask:0xf
	v_addc_co_u32_e32 v39, vcc, -1, v9, vcc
	s_waitcnt lgkmcnt(0)
	s_nop 1
	v_add_f32_dpp v32, v32, v32 row_half_mirror row_mask:0xf bank_mask:0xf
	s_waitcnt lgkmcnt(0)
	s_nop 1
	v_add_f32_dpp v32, v32, v32 row_mirror row_mask:0xf bank_mask:0xf
	ds_bpermute_b32 v33, v29, v32
	s_waitcnt lgkmcnt(0)
	v_add_f32_e32 v32, v32, v33
	ds_bpermute_b32 v33, v30, v32
	s_waitcnt vmcnt(5)
	v_pk_add_f32 v[42:43], v[42:43], 1.0 op_sel_hi:[1,0]
	v_pk_add_f32 v[40:41], v[40:41], 1.0 op_sel_hi:[1,0]
	s_waitcnt vmcnt(3)
	v_pk_mul_f32 v[36:37], v[36:37], v[44:45]
	v_pk_mul_f32 v[34:35], v[34:35], v[46:47]
	v_pk_add_f32 v[44:45], v[50:51], 1.0 op_sel_hi:[1,0]
	v_pk_add_f32 v[46:47], v[48:49], 1.0 op_sel_hi:[1,0]
	s_waitcnt vmcnt(2)
	v_pk_mul_f32 v[48:49], v[64:65], v[52:53]
	v_pk_mul_f32 v[50:51], v[66:67], v[54:55]
	s_waitcnt vmcnt(0)
	v_pk_fma_f32 v[42:43], v[42:43], v[34:35], v[62:63]
	v_pk_fma_f32 v[34:35], v[40:41], v[36:37], v[60:61]
	v_pk_fma_f32 v[40:41], v[44:45], v[50:51], v[58:59]
	v_pk_fma_f32 v[36:37], v[46:47], v[48:49], v[56:57]
	v_cvt_pk_bf16_f32 v34, v34, v35
	v_cvt_pk_bf16_f32 v35, v42, v43
	v_cvt_pk_bf16_f32 v36, v36, v37
	v_cvt_pk_bf16_f32 v37, v40, v41
	global_store_dwordx4 v[38:39], v[34:37], off offset:-3072
	s_cbranch_scc1 .LBB0_670
	s_add_i32 s13, s10, 0xffff8000
	s_lshr_b32 s13, s13, 6
	s_ashr_i32 s12, s10, 13
	s_add_i32 s13, s13, 4
	s_cmp_lt_i32 s10, 0x8000
	s_cselect_b32 s12, s12, s13
	s_mul_hi_i32 s13, s12, 0x9000
	s_mul_i32 s12, s12, 0x9000
	s_add_u32 s14, s30, s12
	s_addc_u32 s15, s31, s13
	s_add_u32 s12, s14, s11
	s_addc_u32 s13, s15, 0
	s_add_u32 s14, s14, s18
	global_load_dwordx4 v[34:37], v[2:3], off offset:16
	global_load_dwordx4 v[38:41], v[2:3], off
	global_load_dwordx4 v[42:45], v31, s[12:13]
	global_load_dwordx4 v[46:49], v31, s[12:13] offset:16
	s_addc_u32 s15, s15, 0
	global_load_dwordx4 v[50:53], v31, s[14:15]
	global_load_dwordx4 v[54:57], v31, s[14:15] offset:16
	s_waitcnt lgkmcnt(0)
	v_add_f32_e32 v32, v32, v33
	v_fmamk_f32 v32, v32, 0x3a800000, v195
	v_rsq_f32_e32 v58, v32
	s_ashr_i32 s11, s10, 31
	s_lshl_b64 s[10:11], s[10:11], 11
	v_lshl_add_u64 v[60:61], v[6:7], 0, s[10:11]
	v_pk_mul_f32 v[24:25], v[24:25], v[58:59] op_sel_hi:[1,0]
	v_pk_mul_f32 v[20:21], v[20:21], v[58:59] op_sel_hi:[1,0]
	v_pk_mul_f32 v[22:23], v[22:23], v[58:59] op_sel_hi:[1,0]
	v_pk_mul_f32 v[18:19], v[18:19], v[58:59] op_sel_hi:[1,0]
	v_pk_mul_f32 v[16:17], v[16:17], v[58:59] op_sel_hi:[1,0]
	v_pk_mul_f32 v[14:15], v[14:15], v[58:59] op_sel_hi:[1,0]
	v_pk_mul_f32 v[12:13], v[12:13], v[58:59] op_sel_hi:[1,0]
	v_pk_mul_f32 v[10:11], v[10:11], v[58:59] op_sel_hi:[1,0]
	s_waitcnt vmcnt(5)
	v_pk_mul_f32 v[18:19], v[18:19], v[34:35]
	s_waitcnt vmcnt(4)
	v_pk_mul_f32 v[20:21], v[20:21], v[38:39]
	v_pk_mul_f32 v[24:25], v[24:25], v[40:41]
	v_pk_mul_f32 v[22:23], v[22:23], v[36:37]
	s_waitcnt vmcnt(3)
	v_pk_add_f32 v[32:33], v[44:45], 1.0 op_sel_hi:[1,0]
	v_pk_add_f32 v[34:35], v[42:43], 1.0 op_sel_hi:[1,0]
	s_waitcnt vmcnt(2)
	v_pk_add_f32 v[36:37], v[48:49], 1.0 op_sel_hi:[1,0]
	v_pk_add_f32 v[38:39], v[46:47], 1.0 op_sel_hi:[1,0]
	s_waitcnt vmcnt(1)
	v_pk_fma_f32 v[24:25], v[32:33], v[24:25], v[52:53]
	v_pk_fma_f32 v[20:21], v[34:35], v[20:21], v[50:51]
	s_waitcnt vmcnt(0)
	v_pk_fma_f32 v[22:23], v[36:37], v[22:23], v[56:57]
	v_pk_fma_f32 v[32:33], v[38:39], v[18:19], v[54:55]
	v_cvt_pk_bf16_f32 v18, v20, v21
	v_cvt_pk_bf16_f32 v19, v24, v25
	v_cvt_pk_bf16_f32 v20, v32, v33
	v_cvt_pk_bf16_f32 v21, v22, v23
	global_store_dwordx4 v[60:61], v[18:21], off
	global_load_dwordx4 v[18:21], v31, s[12:13] offset:2048
	s_nop 0
	global_load_dwordx4 v[22:25], v[2:3], off offset:2048
	global_load_dwordx4 v[32:35], v31, s[12:13] offset:2064
	global_load_dwordx4 v[36:39], v[2:3], off offset:2064
	global_load_dwordx4 v[40:43], v31, s[14:15] offset:2048
	global_load_dwordx4 v[44:47], v31, s[14:15] offset:2064
	s_waitcnt vmcnt(5)
	v_pk_add_f32 v[20:21], v[20:21], 1.0 op_sel_hi:[1,0]
	v_pk_add_f32 v[18:19], v[18:19], 1.0 op_sel_hi:[1,0]
	s_waitcnt vmcnt(4)
	v_pk_mul_f32 v[14:15], v[14:15], v[22:23]
	v_pk_mul_f32 v[16:17], v[16:17], v[24:25]
	s_waitcnt vmcnt(3)
	v_pk_add_f32 v[22:23], v[34:35], 1.0 op_sel_hi:[1,0]
	v_pk_add_f32 v[24:25], v[32:33], 1.0 op_sel_hi:[1,0]
	s_waitcnt vmcnt(2)
	v_pk_mul_f32 v[10:11], v[10:11], v[36:37]
	v_pk_mul_f32 v[12:13], v[12:13], v[38:39]
	s_waitcnt vmcnt(1)
	v_pk_fma_f32 v[16:17], v[20:21], v[16:17], v[42:43]
	v_pk_fma_f32 v[14:15], v[18:19], v[14:15], v[40:41]
	s_waitcnt vmcnt(0)
	v_pk_fma_f32 v[18:19], v[22:23], v[12:13], v[46:47]
	v_pk_fma_f32 v[12:13], v[24:25], v[10:11], v[44:45]
	v_cvt_pk_bf16_f32 v10, v14, v15
	v_cvt_pk_bf16_f32 v11, v16, v17
	v_cvt_pk_bf16_f32 v12, v12, v13
	v_cvt_pk_bf16_f32 v13, v18, v19
	global_store_dwordx4 v[60:61], v[10:13], off offset:1024
	s_branch .LBB0_670

; DI void norm_row16_finish(int m, const f32x4 (&v)[4], float s, const float* gain, const float* mod, int shofs, int scofs, bf16_t* XN, int lane) {
;     const float* mb = mod + (size_t)row_batch(m) * NMOD;
;     const float inv = __builtin_amdgcn_rsqf(s * (1.f / D) + EPS);
; #pragma unroll
;     for (int j = 0; j < 2; ++j) {
;         const int c = 8 * (64 * j + lane);
;         u32x4 w;
; #pragma unroll
;         for (int q = 0; q < 2; ++q) {
;             const f32x4 g4 = *(const f32x4*)(gain + c + 4 * q), sc4 = *(const f32x4*)(mb + scofs + c + 4 * q), sh4 = *(const f32x4*)(mb + shofs + c + 4 * q);
;             const f32x4 o = v[2 * j + q] * inv * g4 * (sc4 + 1.f) + sh4;
;             if (q == 0) { w.x = pk2(o[0], o[1]); w.y = pk2(o[2], o[3]); } else { w.z = pk2(o[0], o[1]); w.w = pk2(o[2], o[3]); }
;         }
;         *(u32x4*)(XN + (size_t)m * D + c) = w;
;     }
; DI void norm_phase_f32w(const float* srcP, const float* srcS, const float* gain, const float* mod, int shofs, int scofs, bf16_t* XN, int wave, int lane) {
;     const int gw = blockIdx.x * 8 + wave, NGW = gridDim.x * 8;
;     for (int m = gw; m < M; m += 2 * NGW) {
;         const int m2 = m + NGW; const bool two = m2 < M; const int mb2 = two ? m2 : m;
;         const float* xa = m < MP ? srcP + (size_t)m * D : srcS + (size_t)(m - MP) * D;
;         const float* xb = mb2 < MP ? srcP + (size_t)mb2 * D : srcS + (size_t)(mb2 - MP) * D;
;         f32x4 va[4], vb[4]; float sa = 0.f, sb = 0.f;
; #pragma unroll
;         for (int j = 0; j < 2; ++j) { const int c = 8 * (64 * j + lane);
;             va[2 * j] = *(const f32x4*)(xa + c); va[2 * j + 1] = *(const f32x4*)(xa + c + 4); vb[2 * j] = *(const f32x4*)(xb + c); vb[2 * j + 1] = *(const f32x4*)(xb + c + 4); }
; #pragma unroll
;         for (int j = 0; j < 4; ++j) { sa += (va[j][0] * va[j][0] + va[j][1] * va[j][1]) + (va[j][2] * va[j][2] + va[j][3] * va[j][3]); sb += (vb[j][0] * vb[j][0] + vb[j][1] * vb[j][1]) + (vb[j][2] * vb[j][2] + vb[j][3] * vb[j][3]); }
; #pragma unroll
;         for (int o = 1; o < 64; o <<= 1) { sa += __shfl_xor(sa, o); sb += __shfl_xor(sb, o); }
;         norm_row16_finish(m, va, sa, gain, mod, shofs, scofs, XN, lane);
;         if (two) norm_row16_finish(m2, vb, sb, gain, mod, shofs, scofs, XN, lane);
.LBB0_678:
	s_add_i32 s20, s35, s6
	s_cmp_lt_i32 s20, 0x8800
	s_cselect_b32 s12, s20, s6
	s_add_i32 s10, s6, 0xffff8000
	s_lshr_b32 s11, s10, 6
	s_ashr_i32 s13, s6, 13
	s_add_i32 s14, s11, 4
	s_cmp_lt_i32 s6, 0x8000
	s_cselect_b32 s11, s7, 0
	s_cselect_b32 s10, s6, s10
	s_cselect_b32 s15, s16, s18
	s_cselect_b32 s21, s17, s19
	s_cselect_b32 s13, s13, s14
	s_lshl_b64 s[10:11], s[10:11], 12
	s_add_u32 s10, s21, s10
	s_addc_u32 s11, s15, s11
	v_lshlrev_b32_e32 v34, 2, v24
	s_waitcnt lgkmcnt(0)
	global_load_dwordx4 v[36:39], v34, s[10:11]
	global_load_dwordx4 v[40:43], v34, s[10:11] offset:16
	global_load_dwordx4 v[4:7], v34, s[10:11] offset:2064
	global_load_dwordx4 v[12:15], v34, s[10:11] offset:2048
	s_add_i32 s10, s12, 0xffff8000
	s_ashr_i32 s11, s12, 31
	s_cmp_lt_i32 s12, 0x8000
	s_cselect_b32 s11, s11, 0
	s_cselect_b32 s10, s12, s10
	s_cselect_b32 s12, s16, s18
	s_cselect_b32 s14, s17, s19
	s_lshl_b64 s[10:11], s[10:11], 12
	s_add_u32 s14, s14, s10
	s_mul_hi_i32 s21, s13, 0x9000
	s_mul_i32 s13, s13, 0x9000
	s_addc_u32 s15, s12, s11
	s_add_u32 s10, s30, s13
	s_addc_u32 s11, s31, s21
	s_add_u32 s12, s10, 0x1000
	s_addc_u32 s13, s11, 0
	global_load_dwordx4 v[44:47], v34, s[12:13]
	global_load_dwordx4 v[48:51], v34, s[12:13] offset:16
	global_load_dwordx4 v[52:55], v[26:27], off
	global_load_dwordx4 v[56:59], v[26:27], off offset:16
	global_load_dwordx4 v[60:63], v34, s[10:11]
	global_load_dwordx4 v[64:67], v34, s[10:11] offset:16
	s_cmp_gt_i32 s20, 0x87ff
	s_waitcnt vmcnt(9)
	v_pk_mul_f32 v[0:1], v[38:39], v[38:39]
	v_pk_mul_f32 v[2:3], v[36:37], v[36:37]
	s_waitcnt vmcnt(8)
	v_pk_mul_f32 v[8:9], v[42:43], v[42:43]
	v_pk_mul_f32 v[10:11], v[40:41], v[40:41]
	v_pk_mov_b32 v[20:21], v[2:3], v[0:1] op_sel:[1,0]
	v_mov_b32_e32 v3, v1
	v_pk_mov_b32 v[0:1], v[10:11], v[8:9] op_sel:[1,0]
	v_mov_b32_e32 v11, v9
	s_waitcnt vmcnt(7)
	v_mul_f32_e32 v19, v4, v4
	s_waitcnt vmcnt(6)
	v_mul_f32_e32 v16, v13, v13
	v_mul_f32_e32 v18, v15, v15
	v_pk_add_f32 v[2:3], v[20:21], v[2:3]
	v_pk_add_f32 v[0:1], v[0:1], v[10:11]
	v_mul_f32_e32 v22, v5, v5
	v_mul_f32_e32 v23, v6, v6
	v_mul_f32_e32 v35, v7, v7
	v_pk_fma_f32 v[8:9], v[12:13], v[12:13], v[16:17] op_sel_hi:[1,1,0]
	v_pk_fma_f32 v[16:17], v[14:15], v[14:15], v[18:19] op_sel_hi:[1,1,0]
	v_pk_add_f32 v[2:3], v[2:3], v[2:3] op_sel:[0,1] op_sel_hi:[1,0]
	v_pk_add_f32 v[0:1], v[0:1], v[0:1] op_sel:[0,1] op_sel_hi:[1,0]
	v_mov_b32_e32 v9, v23
	v_mov_b32_e32 v17, v35
	v_mov_b32_e32 v3, v19
	v_mov_b32_e32 v1, v22
	v_pk_add_f32 v[8:9], v[8:9], v[16:17]
	v_pk_add_f32 v[0:1], v[2:3], v[0:1]
	s_waitcnt vmcnt(5)
	v_pk_add_f32 v[46:47], v[46:47], 1.0 op_sel_hi:[1,0]
	v_pk_add_f32 v[0:1], v[0:1], v[8:9]
	global_load_dwordx4 v[20:23], v34, s[14:15]
	global_load_dwordx4 v[16:19], v34, s[14:15] offset:16
	global_load_dwordx4 v[8:11], v34, s[14:15] offset:2048
	v_add_f32_e32 v0, v0, v1
	v_pk_add_f32 v[44:45], v[44:45], 1.0 op_sel_hi:[1,0]
	s_waitcnt vmcnt(7)
	v_pk_add_f32 v[50:51], v[50:51], 1.0 op_sel_hi:[1,0]
	v_pk_add_f32 v[48:49], v[48:49], 1.0 op_sel_hi:[1,0]
	s_waitcnt lgkmcnt(0)
	s_nop 1
	v_add_f32_dpp v35, v0, v0 quad_perm:[1,0,3,2] row_mask:0xf bank_mask:0xf
	global_load_dwordx4 v[0:3], v34, s[14:15] offset:2064
	s_waitcnt lgkmcnt(0)
	s_nop 1
	v_add_f32_dpp v35, v35, v35 quad_perm:[2,3,0,1] row_mask:0xf bank_mask:0xf
	s_waitcnt lgkmcnt(0)
	s_nop 1
	v_add_f32_dpp v35, v35, v35 row_half_mirror row_mask:0xf bank_mask:0xf
	s_waitcnt lgkmcnt(0)
	s_nop 1
	v_add_f32_dpp v35, v35, v35 row_mirror row_mask:0xf bank_mask:0xf
	ds_bpermute_b32 v70, v31, v35
	v_lshl_add_u64 v[68:69], s[4:5], 0, v[160:161]
	v_add_co_u32_e32 v68, vcc, s71, v68
	s_waitcnt lgkmcnt(0)
	v_add_f32_e32 v35, v35, v70
	ds_bpermute_b32 v70, v32, v35
	v_addc_co_u32_e32 v69, vcc, 0, v69, vcc
	s_waitcnt lgkmcnt(0)
	v_add_f32_e32 v35, v35, v70
	v_fmamk_f32 v35, v35, 0x3a800000, v195
	v_rsq_f32_e32 v70, v35
	s_waitcnt vmcnt(3)
	v_mul_f32_e32 v35, v21, v21
	v_pk_mul_f32 v[38:39], v[38:39], v[70:71] op_sel_hi:[1,0]
	v_pk_mul_f32 v[36:37], v[36:37], v[70:71] op_sel_hi:[1,0]
	v_pk_mul_f32 v[42:43], v[42:43], v[70:71] op_sel_hi:[1,0]
	v_pk_mul_f32 v[40:41], v[40:41], v[70:71] op_sel_hi:[1,0]
	v_pk_mul_f32 v[36:37], v[52:53], v[36:37]
	v_pk_mul_f32 v[38:39], v[54:55], v[38:39]
	v_pk_mul_f32 v[40:41], v[56:57], v[40:41]
	v_pk_mul_f32 v[42:43], v[58:59], v[42:43]
	v_pk_fma_f32 v[38:39], v[46:47], v[38:39], v[62:63]
	v_pk_fma_f32 v[36:37], v[44:45], v[36:37], v[60:61]
	v_pk_fma_f32 v[42:43], v[50:51], v[42:43], v[66:67]
	v_pk_fma_f32 v[40:41], v[48:49], v[40:41], v[64:65]
	v_cvt_pk_bf16_f32 v36, v36, v37
	v_cvt_pk_bf16_f32 v37, v38, v39
	v_cvt_pk_bf16_f32 v38, v40, v41
	v_cvt_pk_bf16_f32 v39, v42, v43
	global_store_dwordx4 v[68:69], v[36:39], off
	global_load_dwordx4 v[38:41], v33, s[12:13]
	s_nop 0
	global_load_dwordx4 v[42:45], v[26:27], off offset:2048
	global_load_dwordx4 v[46:49], v33, s[12:13] offset:16
	global_load_dwordx4 v[50:53], v[26:27], off offset:2064
	global_load_dwordx4 v[54:57], v34, s[10:11] offset:2048
	global_load_dwordx4 v[58:61], v34, s[10:11] offset:2064
	v_mul_f32_e32 v36, v23, v23
	s_waitcnt vmcnt(9)
	v_mul_f32_e32 v37, v17, v17
	v_mul_f32_e32 v62, v19, v19
	s_waitcnt vmcnt(8)
	v_mul_f32_e32 v63, v9, v9
	v_mul_f32_e32 v64, v11, v11
	v_fmac_f32_e32 v35, v20, v20
	v_fmac_f32_e32 v36, v22, v22
	v_fmac_f32_e32 v37, v16, v16
	v_fmac_f32_e32 v62, v18, v18
	s_waitcnt vmcnt(7)
; DI void norm_row16_finish(int m, const f32x4 (&v)[4], float s, const float* gain, const float* mod, int shofs, int scofs, bf16_t* XN, int lane) {
;     const float* mb = mod + (size_t)row_batch(m) * NMOD;
;     const float inv = __builtin_amdgcn_rsqf(s * (1.f / D) + EPS);
; #pragma unroll
;     for (int j = 0; j < 2; ++j) {
;         const int c = 8 * (64 * j + lane);
;         u32x4 w;
; #pragma unroll
;         for (int q = 0; q < 2; ++q) {
;             const f32x4 g4 = *(const f32x4*)(gain + c + 4 * q), sc4 = *(const f32x4*)(mb + scofs + c + 4 * q), sh4 = *(const f32x4*)(mb + shofs + c + 4 * q);
;             const f32x4 o = v[2 * j + q] * inv * g4 * (sc4 + 1.f) + sh4;
;             if (q == 0) { w.x = pk2(o[0], o[1]); w.y = pk2(o[2], o[3]); } else { w.z = pk2(o[0], o[1]); w.w = pk2(o[2], o[3]); }
;         }
;         *(u32x4*)(XN + (size_t)m * D + c) = w;
;     }
; DI void norm_phase_f32w(const float* srcP, const float* srcS, const float* gain, const float* mod, int shofs, int scofs, bf16_t* XN, int wave, int lane) {
;     const int gw = blockIdx.x * 8 + wave, NGW = gridDim.x * 8;
;     for (int m = gw; m < M; m += 2 * NGW) {
;         const int m2 = m + NGW; const bool two = m2 < M; const int mb2 = two ? m2 : m;
;         const float* xa = m < MP ? srcP + (size_t)m * D : srcS + (size_t)(m - MP) * D;
;         const float* xb = mb2 < MP ? srcP + (size_t)mb2 * D : srcS + (size_t)(mb2 - MP) * D;
;         f32x4 va[4], vb[4]; float sa = 0.f, sb = 0.f;
; #pragma unroll
;         for (int j = 0; j < 2; ++j) { const int c = 8 * (64 * j + lane);
;             va[2 * j] = *(const f32x4*)(xa + c); va[2 * j + 1] = *(const f32x4*)(xa + c + 4); vb[2 * j] = *(const f32x4*)(xb + c); vb[2 * j + 1] = *(const f32x4*)(xb + c + 4); }
; #pragma unroll
;         for (int j = 0; j < 4; ++j) { sa += (va[j][0] * va[j][0] + va[j][1] * va[j][1]) + (va[j][2] * va[j][2] + va[j][3] * va[j][3]); sb += (vb[j][0] * vb[j][0] + vb[j][1] * vb[j][1]) + (vb[j][2] * vb[j][2] + vb[j][3] * vb[j][3]); }
; #pragma unroll
;         for (int o = 1; o < 64; o <<= 1) { sa += __shfl_xor(sa, o); sb += __shfl_xor(sb, o); }
;         norm_row16_finish(m, va, sa, gain, mod, shofs, scofs, XN, lane);
;         if (two) norm_row16_finish(m2, vb, sb, gain, mod, shofs, scofs, XN, lane);
;     }
	v_mul_f32_e32 v65, v1, v1
	v_mul_f32_e32 v66, v3, v3
	v_fmac_f32_e32 v63, v8, v8
	v_fmac_f32_e32 v64, v10, v10
	v_add_f32_e32 v35, v35, v36
	v_add_f32_e32 v36, v37, v62
	v_fmac_f32_e32 v65, v0, v0
	v_fmac_f32_e32 v66, v2, v2
	v_add_f32_e32 v37, v63, v64
	v_add_f32_e32 v35, v35, v36
	v_add_f32_e32 v62, v65, v66
	v_add_f32_e32 v35, v35, v37
	v_add_f32_e32 v35, v35, v62
	v_pk_mul_f32 v[14:15], v[14:15], v[70:71] op_sel_hi:[1,0]
	v_pk_mul_f32 v[12:13], v[12:13], v[70:71] op_sel_hi:[1,0]
	v_pk_mul_f32 v[6:7], v[6:7], v[70:71] op_sel_hi:[1,0]
	v_pk_mul_f32 v[4:5], v[4:5], v[70:71] op_sel_hi:[1,0]
	s_waitcnt lgkmcnt(0)
	s_nop 1
	v_add_f32_dpp v35, v35, v35 quad_perm:[1,0,3,2] row_mask:0xf bank_mask:0xf
	s_waitcnt lgkmcnt(0)
	s_nop 1
	v_add_f32_dpp v35, v35, v35 quad_perm:[2,3,0,1] row_mask:0xf bank_mask:0xf
	s_waitcnt lgkmcnt(0)
	s_nop 1
	v_add_f32_dpp v35, v35, v35 row_half_mirror row_mask:0xf bank_mask:0xf
	s_waitcnt lgkmcnt(0)
	s_nop 1
	v_add_f32_dpp v35, v35, v35 row_mirror row_mask:0xf bank_mask:0xf
	ds_bpermute_b32 v36, v31, v35
	s_waitcnt lgkmcnt(0)
	v_add_f32_e32 v35, v35, v36
	ds_bpermute_b32 v36, v32, v35
	s_waitcnt vmcnt(5)
	v_pk_add_f32 v[40:41], v[40:41], 1.0 op_sel_hi:[1,0]
	v_pk_add_f32 v[38:39], v[38:39], 1.0 op_sel_hi:[1,0]
	s_waitcnt vmcnt(4)
	v_pk_mul_f32 v[12:13], v[12:13], v[42:43]
	v_pk_mul_f32 v[14:15], v[14:15], v[44:45]
	s_waitcnt vmcnt(3)
	v_pk_add_f32 v[42:43], v[48:49], 1.0 op_sel_hi:[1,0]
	v_pk_add_f32 v[44:45], v[46:47], 1.0 op_sel_hi:[1,0]
	s_waitcnt vmcnt(2)
	v_pk_mul_f32 v[4:5], v[4:5], v[50:51]
	v_pk_mul_f32 v[6:7], v[6:7], v[52:53]
	s_waitcnt vmcnt(1)
	v_pk_fma_f32 v[14:15], v[40:41], v[14:15], v[56:57]
	v_pk_fma_f32 v[12:13], v[38:39], v[12:13], v[54:55]
	s_waitcnt vmcnt(0)
	v_pk_fma_f32 v[38:39], v[42:43], v[6:7], v[60:61]
	v_pk_fma_f32 v[6:7], v[44:45], v[4:5], v[58:59]
	v_cvt_pk_bf16_f32 v4, v12, v13
	v_cvt_pk_bf16_f32 v5, v14, v15
	v_cvt_pk_bf16_f32 v6, v6, v7
	v_cvt_pk_bf16_f32 v7, v38, v39
	global_store_dwordx4 v[68:69], v[4:7], off offset:1024
	s_cbranch_scc1 .LBB0_677
	s_add_i32 s11, s20, 0xffff8000
	s_lshr_b32 s11, s11, 6
	s_ashr_i32 s10, s20, 13
	s_add_i32 s11, s11, 4
	s_cmp_lt_i32 s20, 0x8000
	s_cselect_b32 s10, s10, s11
	s_mul_hi_i32 s11, s10, 0x9000
	s_mul_i32 s10, s10, 0x9000
	s_add_u32 s10, s30, s10
	s_addc_u32 s11, s31, s11
	s_add_u32 s12, s10, 0x1000
	global_load_dwordx4 v[4:7], v[26:27], off offset:16
	global_load_dwordx4 v[12:15], v[26:27], off
	s_addc_u32 s13, s11, 0
	global_load_dwordx4 v[38:41], v34, s[12:13]
	global_load_dwordx4 v[42:45], v34, s[12:13] offset:16
	global_load_dwordx4 v[46:49], v34, s[10:11]
	global_load_dwordx4 v[50:53], v34, s[10:11] offset:16
	s_waitcnt lgkmcnt(0)
	v_add_f32_e32 v35, v35, v36
	v_fmamk_f32 v35, v35, 0x3a800000, v195
	v_rsq_f32_e32 v54, v35
	v_lshl_add_u64 v[36:37], s[8:9], 0, v[160:161]
	v_add_co_u32_e32 v56, vcc, s71, v36
	v_pk_mul_f32 v[22:23], v[22:23], v[54:55] op_sel_hi:[1,0]
	v_pk_mul_f32 v[20:21], v[20:21], v[54:55] op_sel_hi:[1,0]
	v_pk_mul_f32 v[18:19], v[18:19], v[54:55] op_sel_hi:[1,0]
	v_pk_mul_f32 v[16:17], v[16:17], v[54:55] op_sel_hi:[1,0]
	v_addc_co_u32_e32 v57, vcc, 0, v37, vcc
	v_pk_mul_f32 v[10:11], v[10:11], v[54:55] op_sel_hi:[1,0]
	v_pk_mul_f32 v[8:9], v[8:9], v[54:55] op_sel_hi:[1,0]
	v_pk_mul_f32 v[2:3], v[2:3], v[54:55] op_sel_hi:[1,0]
	v_pk_mul_f32 v[0:1], v[0:1], v[54:55] op_sel_hi:[1,0]
	s_waitcnt vmcnt(5)
	v_pk_mul_f32 v[6:7], v[18:19], v[6:7]
	s_waitcnt vmcnt(4)
	v_pk_mul_f32 v[14:15], v[22:23], v[14:15]
	v_pk_mul_f32 v[12:13], v[20:21], v[12:13]
	v_pk_mul_f32 v[4:5], v[16:17], v[4:5]
	s_waitcnt vmcnt(3)
	v_pk_add_f32 v[16:17], v[40:41], 1.0 op_sel_hi:[1,0]
	v_pk_add_f32 v[18:19], v[38:39], 1.0 op_sel_hi:[1,0]
	s_waitcnt vmcnt(2)
	v_pk_add_f32 v[20:21], v[44:45], 1.0 op_sel_hi:[1,0]
	v_pk_add_f32 v[22:23], v[42:43], 1.0 op_sel_hi:[1,0]
	s_waitcnt vmcnt(1)
	v_pk_fma_f32 v[14:15], v[16:17], v[14:15], v[48:49]
	v_pk_fma_f32 v[12:13], v[18:19], v[12:13], v[46:47]
	s_waitcnt vmcnt(0)
	v_pk_fma_f32 v[16:17], v[20:21], v[6:7], v[52:53]
	v_pk_fma_f32 v[6:7], v[22:23], v[4:5], v[50:51]
	v_cvt_pk_bf16_f32 v4, v12, v13
	v_cvt_pk_bf16_f32 v5, v14, v15
	v_cvt_pk_bf16_f32 v6, v6, v7
	v_cvt_pk_bf16_f32 v7, v16, v17
	global_store_dwordx4 v[56:57], v[4:7], off
	global_load_dwordx4 v[4:7], v33, s[12:13]
	s_nop 0
	global_load_dwordx4 v[12:15], v[26:27], off offset:2048
	global_load_dwordx4 v[16:19], v33, s[12:13] offset:16
	global_load_dwordx4 v[20:23], v[26:27], off offset:2064
	global_load_dwordx4 v[36:39], v34, s[10:11] offset:2048
	global_load_dwordx4 v[40:43], v34, s[10:11] offset:2064
	s_waitcnt vmcnt(5)
	v_pk_add_f32 v[6:7], v[6:7], 1.0 op_sel_hi:[1,0]
	v_pk_add_f32 v[4:5], v[4:5], 1.0 op_sel_hi:[1,0]
	s_waitcnt vmcnt(4)
	v_pk_mul_f32 v[10:11], v[10:11], v[14:15]
	v_pk_mul_f32 v[8:9], v[8:9], v[12:13]
	s_waitcnt vmcnt(3)
	v_pk_add_f32 v[12:13], v[18:19], 1.0 op_sel_hi:[1,0]
	v_pk_add_f32 v[14:15], v[16:17], 1.0 op_sel_hi:[1,0]
	s_waitcnt vmcnt(2)
	v_pk_mul_f32 v[2:3], v[2:3], v[22:23]
	v_pk_mul_f32 v[0:1], v[0:1], v[20:21]
	s_waitcnt vmcnt(1)
	v_pk_fma_f32 v[6:7], v[6:7], v[10:11], v[38:39]
	v_pk_fma_f32 v[4:5], v[4:5], v[8:9], v[36:37]
	s_waitcnt vmcnt(0)
	v_pk_fma_f32 v[8:9], v[12:13], v[2:3], v[42:43]
	v_pk_fma_f32 v[2:3], v[14:15], v[0:1], v[40:41]
	v_cvt_pk_bf16_f32 v0, v4, v5
	v_cvt_pk_bf16_f32 v1, v6, v7
	v_cvt_pk_bf16_f32 v2, v2, v3
	v_cvt_pk_bf16_f32 v3, v8, v9
	global_store_dwordx4 v[56:57], v[0:3], off offset:1024
	s_branch .LBB0_677
